# GEMM super-phase: closing barrier directly behind the last MFMA, setprio 0 after it
# speedup vs baseline: 1.0720x; 1.0720x over previous
; #define PG8_STAGE(bufoff, gbase, voff) do { _Pragma("unroll") for (int _i = 0; _i < 2; ++_i) \
;         __builtin_amdgcn_global_load_lds((const unsigned*)((const char*)(gbase) + (voff)[_i]), (PG8_LAS unsigned*)(lds + (bufoff) + ldsw + _i * 8192), 16, 0, 0); } while (0)
; #define PG8_LDA(dst, b, h) do { _Pragma("unroll") for (int m = 0; m < 4; ++m) _Pragma("unroll") for (int k = 0; k < 2; ++k) dst[m][k] = *(const PG8_LAS bf16x8*)(lds + PG8_SA(b, h) + aoff + m * 2048 + k * 1024); } while (0)
; #define PG8_LDB(dst, b, h) do { _Pragma("unroll") for (int n = 0; n < 2; ++n) _Pragma("unroll") for (int k = 0; k < 2; ++k) dst[n][k] = *(const PG8_LAS bf16x8*)(lds + PG8_SB(b, h) + boff + n * 2048 + k * 1024); } while (0)
; #define PG8_MMA(ai, bj, At, Bt) do { __builtin_amdgcn_s_setprio(1); _Pragma("unroll") for (int m = 0; m < 4; ++m) _Pragma("unroll") for (int n = 0; n < 2; ++n) _Pragma("unroll") for (int k = 0; k < 2; ++k) \
;         acc[ai][bj][m][n] = __builtin_amdgcn_mfma_f32_16x16x32_bf16(Bt[n][k], At[m][k], acc[ai][bj][m][n], 0, 0, 0); __builtin_amdgcn_s_setprio(0); } while (0)
; #define PG8_WAIT_V(n) asm volatile("s_waitcnt vmcnt(" #n ")" ::: "memory")
; #define PG8_WAIT_L(n) asm volatile("s_waitcnt lgkmcnt(" #n ")" ::: "memory")
; #define PG8_BAR __builtin_amdgcn_s_barrier()
; #define PG8_SCHED __builtin_amdgcn_sched_barrier(0)
; template <class Epi, class Sched, bool ALIGN_EPI = false, bool SP2 = false>
; __device__ __forceinline__ void gemm_phase(PG8_LAS unsigned char* lds, const Gemm g, const Sched& S, const Epi& E, const int tid) {
;     ...
;             const char* a2 = last ? nA : cA + (size_t)(t + 2) * kstep; const char* b2 = last ? nB : cB + (size_t)(t + 2) * kstep;
;             const char* a3 = a2 + kstep; const char* b3 = b2 + kstep;
;             if (last && has_next) S.a_ready(nxt);
;             if constexpr (SP2) {
;             PG8_LDB(B0, 0, 0); PG8_LDB(B1, 0, 1); PG8_SCHED; PG8_LDA(At, 0, 0); PG8_STAGE(PG8_SA(1, 1), a1 + hstep, voffA);
;             PG8_WAIT_V(8); PG8_WAIT_L(0); PG8_BAR; PG8_MMA(0, 0, At, B0); PG8_MMA(0, 1, At, B1); PG8_BAR; PG8_SCHED;
;             PG8_LDA(At, 0, 1); PG8_STAGE(PG8_SB(0, 0), b2, voffB); PG8_STAGE(PG8_SB(0, 1), b2 + hstep, voffB); PG8_STAGE(PG8_SA(0, 0), a2, voffA);
;             PG8_WAIT_V(8); PG8_WAIT_L(0); PG8_BAR; PG8_MMA(1, 0, At, B0); PG8_MMA(1, 1, At, B1); PG8_BAR; PG8_SCHED;
.LBB0_87:
	s_add_u32 s38, s22, s68
	s_addc_u32 s39, s23, s69
	s_add_u32 s38, s38, 0x100
	s_addc_u32 s39, s39, 0
	s_add_u32 s50, s89, s68
	s_addc_u32 s51, s90, s69
	s_add_i32 s92, 0, 0x10000
	s_cmpk_eq_i32 s68, 0x700
	s_cselect_b32 s73, s15, s39
	s_cselect_b32 s72, s86, s38
	v_add_u32_e32 v150, s92, v153
	s_cselect_b32 s71, s87, s51
	s_cselect_b32 s70, s88, s50
	s_add_i32 s38, 0, 0x14000
	ds_read_b128 v[170:173], v150
	ds_read_b128 v[174:177], v150 offset:1024
	ds_read_b128 v[178:181], v150 offset:2048
	ds_read_b128 v[182:185], v150 offset:3072
	v_add_u32_e32 v150, s38, v153
	ds_read_b128 v[186:189], v150
	ds_read_b128 v[190:193], v150 offset:1024
	ds_read_b128 v[206:209], v150 offset:2048
	ds_read_b128 v[210:213], v150 offset:3072
	v_lshl_add_u64 v[246:247], v[146:147], 0, s[68:69]
	s_add_i32 m0, s76, 0xc000
	ds_read_b128 v[214:217], v167
	ds_read_b128 v[218:221], v167 offset:1024
	ds_read_b128 v[222:225], v167 offset:2048
	ds_read_b128 v[226:229], v167 offset:3072
	ds_read_b128 v[230:233], v167 offset:4096
	ds_read_b128 v[234:237], v167 offset:5120
	ds_read_b128 v[238:241], v167 offset:6144
	ds_read_b128 v[242:245], v167 offset:7168
	global_load_lds_dwordx4 v[246:247], off
	v_lshl_add_u64 v[246:247], v[148:149], 0, s[68:69]
	s_add_i32 m0, s76, 0xe000
	s_nop 0
	global_load_lds_dwordx4 v[246:247], off
	s_waitcnt vmcnt(8)
	s_waitcnt lgkmcnt(0)
	s_setprio 1
	s_barrier
	v_mfma_f32_16x16x32_bf16 v[126:129], v[170:173], v[214:217], v[126:129]
	v_mfma_f32_16x16x32_bf16 v[122:125], v[178:181], v[214:217], v[122:125]
	v_mfma_f32_16x16x32_bf16 v[110:113], v[170:173], v[222:225], v[110:113]
	v_mfma_f32_16x16x32_bf16 v[106:109], v[178:181], v[222:225], v[106:109]
	v_mfma_f32_16x16x32_bf16 v[94:97], v[170:173], v[230:233], v[94:97]
	v_mfma_f32_16x16x32_bf16 v[90:93], v[178:181], v[230:233], v[90:93]
	v_mfma_f32_16x16x32_bf16 v[78:81], v[170:173], v[238:241], v[78:81]
	v_mfma_f32_16x16x32_bf16 v[74:77], v[178:181], v[238:241], v[74:77]
	v_mfma_f32_16x16x32_bf16 v[126:129], v[174:177], v[218:221], v[126:129]
	v_mfma_f32_16x16x32_bf16 v[122:125], v[182:185], v[218:221], v[122:125]
	v_mfma_f32_16x16x32_bf16 v[110:113], v[174:177], v[226:229], v[110:113]
	v_mfma_f32_16x16x32_bf16 v[106:109], v[182:185], v[226:229], v[106:109]
	v_mfma_f32_16x16x32_bf16 v[94:97], v[174:177], v[234:237], v[94:97]
	v_mfma_f32_16x16x32_bf16 v[90:93], v[182:185], v[234:237], v[90:93]
	v_mfma_f32_16x16x32_bf16 v[78:81], v[174:177], v[242:245], v[78:81]
	v_mfma_f32_16x16x32_bf16 v[74:77], v[182:185], v[242:245], v[74:77]
	v_mfma_f32_16x16x32_bf16 v[118:121], v[186:189], v[214:217], v[118:121]
	v_mfma_f32_16x16x32_bf16 v[114:117], v[206:209], v[214:217], v[114:117]
	v_mfma_f32_16x16x32_bf16 v[102:105], v[186:189], v[222:225], v[102:105]
	v_mfma_f32_16x16x32_bf16 v[98:101], v[206:209], v[222:225], v[98:101]
	v_mfma_f32_16x16x32_bf16 v[86:89], v[186:189], v[230:233], v[86:89]
	v_mfma_f32_16x16x32_bf16 v[82:85], v[206:209], v[230:233], v[82:85]
	v_mfma_f32_16x16x32_bf16 v[70:73], v[186:189], v[238:241], v[70:73]
	v_mfma_f32_16x16x32_bf16 v[66:69], v[206:209], v[238:241], v[66:69]
	v_mfma_f32_16x16x32_bf16 v[118:121], v[190:193], v[218:221], v[118:121]
	v_mfma_f32_16x16x32_bf16 v[114:117], v[210:213], v[218:221], v[114:117]
	v_mfma_f32_16x16x32_bf16 v[102:105], v[190:193], v[226:229], v[102:105]
	v_mfma_f32_16x16x32_bf16 v[98:101], v[210:213], v[226:229], v[98:101]
	v_mfma_f32_16x16x32_bf16 v[86:89], v[190:193], v[234:237], v[86:89]
	v_mfma_f32_16x16x32_bf16 v[82:85], v[210:213], v[234:237], v[82:85]
	v_mfma_f32_16x16x32_bf16 v[70:73], v[190:193], v[242:245], v[70:73]
	v_mfma_f32_16x16x32_bf16 v[66:69], v[210:213], v[242:245], v[66:69]
	s_barrier
	s_setprio 0
	s_add_i32 s39, s92, s75
	v_lshl_add_u64 v[246:247], s[70:71], 0, v[0:1]
	s_mov_b32 m0, s39
	ds_read_b128 v[214:217], v167 offset:16384
	ds_read_b128 v[218:221], v167 offset:17408
	ds_read_b128 v[222:225], v167 offset:18432
	ds_read_b128 v[226:229], v167 offset:19456
	ds_read_b128 v[230:233], v167 offset:20480
	ds_read_b128 v[234:237], v167 offset:21504
	ds_read_b128 v[238:241], v167 offset:22528
	ds_read_b128 v[242:245], v167 offset:23552
	global_load_lds_dwordx4 v[246:247], off
	s_add_i32 m0, s39, 0x2000
	s_add_u32 s50, s70, 0x40000
	v_lshl_add_u64 v[248:249], s[70:71], 0, v[130:131]
	s_addc_u32 s51, s71, 0
	s_add_i32 s38, s38, s75
	global_load_lds_dwordx4 v[248:249], off
	v_lshl_add_u64 v[250:251], s[50:51], 0, v[0:1]
	s_mov_b32 m0, s38
	v_lshl_add_u64 v[252:253], s[72:73], 0, v[132:133]
	global_load_lds_dwordx4 v[250:251], off
	v_lshl_add_u64 v[250:251], s[50:51], 0, v[130:131]
	s_add_i32 m0, s38, 0x2000
	s_nop 0
	global_load_lds_dwordx4 v[250:251], off
	v_lshl_add_u64 v[250:251], s[72:73], 0, v[134:135]
	s_mov_b32 m0, s76
	s_nop 0
	global_load_lds_dwordx4 v[250:251], off
	s_mov_b32 m0, s77
	s_nop 0
	global_load_lds_dwordx4 v[252:253], off
	s_waitcnt vmcnt(8)
	s_waitcnt lgkmcnt(0)
	s_setprio 1
	s_barrier
; #define PG8_STAGE(bufoff, gbase, voff) do { _Pragma("unroll") for (int _i = 0; _i < 2; ++_i) \
;         __builtin_amdgcn_global_load_lds((const unsigned*)((const char*)(gbase) + (voff)[_i]), (PG8_LAS unsigned*)(lds + (bufoff) + ldsw + _i * 8192), 16, 0, 0); } while (0)
; #define PG8_LDA(dst, b, h) do { _Pragma("unroll") for (int m = 0; m < 4; ++m) _Pragma("unroll") for (int k = 0; k < 2; ++k) dst[m][k] = *(const PG8_LAS bf16x8*)(lds + PG8_SA(b, h) + aoff + m * 2048 + k * 1024); } while (0)
; #define PG8_LDB(dst, b, h) do { _Pragma("unroll") for (int n = 0; n < 2; ++n) _Pragma("unroll") for (int k = 0; k < 2; ++k) dst[n][k] = *(const PG8_LAS bf16x8*)(lds + PG8_SB(b, h) + boff + n * 2048 + k * 1024); } while (0)
; #define PG8_MMA(ai, bj, At, Bt) do { __builtin_amdgcn_s_setprio(1); _Pragma("unroll") for (int m = 0; m < 4; ++m) _Pragma("unroll") for (int n = 0; n < 2; ++n) _Pragma("unroll") for (int k = 0; k < 2; ++k) \
;         acc[ai][bj][m][n] = __builtin_amdgcn_mfma_f32_16x16x32_bf16(Bt[n][k], At[m][k], acc[ai][bj][m][n], 0, 0, 0); __builtin_amdgcn_s_setprio(0); } while (0)
; #define PG8_WAIT_V(n) asm volatile("s_waitcnt vmcnt(" #n ")" ::: "memory")
; #define PG8_WAIT_L(n) asm volatile("s_waitcnt lgkmcnt(" #n ")" ::: "memory")
; #define PG8_BAR __builtin_amdgcn_s_barrier()
; #define PG8_SCHED __builtin_amdgcn_sched_barrier(0)
; template <class Epi, class Sched, bool ALIGN_EPI = false, bool SP2 = false>
; __device__ __forceinline__ void gemm_phase(PG8_LAS unsigned char* lds, const Gemm g, const Sched& S, const Epi& E, const int tid) {
;     ...
;             PG8_WAIT_V(8); PG8_WAIT_L(0); PG8_BAR; PG8_MMA(1, 0, At, B0); PG8_MMA(1, 1, At, B1); PG8_BAR; PG8_SCHED;
;             PG8_LDB(B0, 1, 0); PG8_LDB(B1, 1, 1); PG8_SCHED; PG8_LDA(At, 1, 0); PG8_STAGE(PG8_SA(0, 1), a2 + hstep, voffA);
;             PG8_WAIT_V(8); PG8_WAIT_L(0); PG8_BAR; PG8_MMA(0, 0, At, B0); PG8_MMA(0, 1, At, B1); PG8_BAR; PG8_SCHED;
	v_mfma_f32_16x16x32_bf16 v[62:65], v[170:173], v[214:217], v[62:65]
	v_mfma_f32_16x16x32_bf16 v[58:61], v[178:181], v[214:217], v[58:61]
	v_mfma_f32_16x16x32_bf16 v[46:49], v[170:173], v[222:225], v[46:49]
	v_mfma_f32_16x16x32_bf16 v[42:45], v[178:181], v[222:225], v[42:45]
	v_mfma_f32_16x16x32_bf16 v[30:33], v[170:173], v[230:233], v[30:33]
	v_mfma_f32_16x16x32_bf16 v[26:29], v[178:181], v[230:233], v[26:29]
	v_mfma_f32_16x16x32_bf16 v[14:17], v[170:173], v[238:241], v[14:17]
	v_mfma_f32_16x16x32_bf16 v[10:13], v[178:181], v[238:241], v[10:13]
	v_mfma_f32_16x16x32_bf16 v[62:65], v[174:177], v[218:221], v[62:65]
	v_mfma_f32_16x16x32_bf16 v[58:61], v[182:185], v[218:221], v[58:61]
	v_mfma_f32_16x16x32_bf16 v[46:49], v[174:177], v[226:229], v[46:49]
	v_mfma_f32_16x16x32_bf16 v[42:45], v[182:185], v[226:229], v[42:45]
	v_mfma_f32_16x16x32_bf16 v[30:33], v[174:177], v[234:237], v[30:33]
	v_mfma_f32_16x16x32_bf16 v[26:29], v[182:185], v[234:237], v[26:29]
	v_mfma_f32_16x16x32_bf16 v[14:17], v[174:177], v[242:245], v[14:17]
	v_mfma_f32_16x16x32_bf16 v[10:13], v[182:185], v[242:245], v[10:13]
	v_mfma_f32_16x16x32_bf16 v[54:57], v[186:189], v[214:217], v[54:57]
	v_mfma_f32_16x16x32_bf16 v[50:53], v[206:209], v[214:217], v[50:53]
	v_mfma_f32_16x16x32_bf16 v[38:41], v[186:189], v[222:225], v[38:41]
	v_mfma_f32_16x16x32_bf16 v[34:37], v[206:209], v[222:225], v[34:37]
	v_mfma_f32_16x16x32_bf16 v[22:25], v[186:189], v[230:233], v[22:25]
	v_mfma_f32_16x16x32_bf16 v[18:21], v[206:209], v[230:233], v[18:21]
	v_mfma_f32_16x16x32_bf16 v[6:9], v[186:189], v[238:241], v[6:9]
	v_mfma_f32_16x16x32_bf16 v[2:5], v[206:209], v[238:241], v[2:5]
	v_mfma_f32_16x16x32_bf16 v[54:57], v[190:193], v[218:221], v[54:57]
	v_mfma_f32_16x16x32_bf16 v[50:53], v[210:213], v[218:221], v[50:53]
	v_mfma_f32_16x16x32_bf16 v[38:41], v[190:193], v[226:229], v[38:41]
	v_mfma_f32_16x16x32_bf16 v[34:37], v[210:213], v[226:229], v[34:37]
	v_mfma_f32_16x16x32_bf16 v[22:25], v[190:193], v[234:237], v[22:25]
	v_mfma_f32_16x16x32_bf16 v[18:21], v[210:213], v[234:237], v[18:21]
	v_mfma_f32_16x16x32_bf16 v[6:9], v[190:193], v[242:245], v[6:9]
	v_mfma_f32_16x16x32_bf16 v[2:5], v[210:213], v[242:245], v[2:5]
	s_barrier
	s_setprio 0
	s_add_i32 s38, 0, 0x18000
	v_add_u32_e32 v150, s38, v153
	s_add_i32 s39, 0, 0x1c000
	ds_read_b128 v[170:173], v150
	ds_read_b128 v[174:177], v150 offset:1024
	ds_read_b128 v[178:181], v150 offset:2048
	ds_read_b128 v[182:185], v150 offset:3072
	v_add_u32_e32 v150, s39, v153
	ds_read_b128 v[186:189], v150
	ds_read_b128 v[190:193], v150 offset:1024
	ds_read_b128 v[206:209], v150 offset:2048
	ds_read_b128 v[210:213], v150 offset:3072
	s_add_u32 s50, s72, 0x40000
	s_addc_u32 s51, s73, 0
	s_mov_b32 m0, s78
	v_lshl_add_u64 v[194:195], s[50:51], 0, v[134:135]
	ds_read_b128 v[214:217], v167 offset:32768
	ds_read_b128 v[218:221], v167 offset:33792
	ds_read_b128 v[222:225], v167 offset:34816
	ds_read_b128 v[226:229], v167 offset:35840
	ds_read_b128 v[230:233], v167 offset:36864
	ds_read_b128 v[234:237], v167 offset:37888
	ds_read_b128 v[238:241], v167 offset:38912
	ds_read_b128 v[242:245], v167 offset:39936
	global_load_lds_dwordx4 v[194:195], off
	v_lshl_add_u64 v[194:195], s[50:51], 0, v[132:133]
	s_mov_b32 m0, s79
	s_nop 0
	global_load_lds_dwordx4 v[194:195], off
	s_waitcnt vmcnt(8)
	s_waitcnt lgkmcnt(0)
	s_setprio 1
	s_barrier
	v_mfma_f32_16x16x32_bf16 v[126:129], v[170:173], v[214:217], v[126:129]
	v_mfma_f32_16x16x32_bf16 v[122:125], v[178:181], v[214:217], v[122:125]
	v_mfma_f32_16x16x32_bf16 v[110:113], v[170:173], v[222:225], v[110:113]
	v_mfma_f32_16x16x32_bf16 v[106:109], v[178:181], v[222:225], v[106:109]
	v_mfma_f32_16x16x32_bf16 v[94:97], v[170:173], v[230:233], v[94:97]
	v_mfma_f32_16x16x32_bf16 v[90:93], v[178:181], v[230:233], v[90:93]
	v_mfma_f32_16x16x32_bf16 v[78:81], v[170:173], v[238:241], v[78:81]
	v_mfma_f32_16x16x32_bf16 v[74:77], v[178:181], v[238:241], v[74:77]
	v_mfma_f32_16x16x32_bf16 v[126:129], v[174:177], v[218:221], v[126:129]
	v_mfma_f32_16x16x32_bf16 v[122:125], v[182:185], v[218:221], v[122:125]
	v_mfma_f32_16x16x32_bf16 v[110:113], v[174:177], v[226:229], v[110:113]
	v_mfma_f32_16x16x32_bf16 v[106:109], v[182:185], v[226:229], v[106:109]
	v_mfma_f32_16x16x32_bf16 v[94:97], v[174:177], v[234:237], v[94:97]
	v_mfma_f32_16x16x32_bf16 v[90:93], v[182:185], v[234:237], v[90:93]
	v_mfma_f32_16x16x32_bf16 v[78:81], v[174:177], v[242:245], v[78:81]
	v_mfma_f32_16x16x32_bf16 v[74:77], v[182:185], v[242:245], v[74:77]
	v_mfma_f32_16x16x32_bf16 v[118:121], v[186:189], v[214:217], v[118:121]
	v_mfma_f32_16x16x32_bf16 v[114:117], v[206:209], v[214:217], v[114:117]
	v_mfma_f32_16x16x32_bf16 v[102:105], v[186:189], v[222:225], v[102:105]
	v_mfma_f32_16x16x32_bf16 v[98:101], v[206:209], v[222:225], v[98:101]
	v_mfma_f32_16x16x32_bf16 v[86:89], v[186:189], v[230:233], v[86:89]
	v_mfma_f32_16x16x32_bf16 v[82:85], v[206:209], v[230:233], v[82:85]
	v_mfma_f32_16x16x32_bf16 v[70:73], v[186:189], v[238:241], v[70:73]
	v_mfma_f32_16x16x32_bf16 v[66:69], v[206:209], v[238:241], v[66:69]
	v_mfma_f32_16x16x32_bf16 v[118:121], v[190:193], v[218:221], v[118:121]
	v_mfma_f32_16x16x32_bf16 v[114:117], v[210:213], v[218:221], v[114:117]
	v_mfma_f32_16x16x32_bf16 v[102:105], v[190:193], v[226:229], v[102:105]
	v_mfma_f32_16x16x32_bf16 v[98:101], v[210:213], v[226:229], v[98:101]
	v_mfma_f32_16x16x32_bf16 v[86:89], v[190:193], v[234:237], v[86:89]
	v_mfma_f32_16x16x32_bf16 v[82:85], v[210:213], v[234:237], v[82:85]
	v_mfma_f32_16x16x32_bf16 v[70:73], v[190:193], v[242:245], v[70:73]
	v_mfma_f32_16x16x32_bf16 v[66:69], v[210:213], v[242:245], v[66:69]
	s_barrier
; #define PG8_STAGE(bufoff, gbase, voff) do { _Pragma("unroll") for (int _i = 0; _i < 2; ++_i) \
;         __builtin_amdgcn_global_load_lds((const unsigned*)((const char*)(gbase) + (voff)[_i]), (PG8_LAS unsigned*)(lds + (bufoff) + ldsw + _i * 8192), 16, 0, 0); } while (0)
; #define PG8_LDA(dst, b, h) do { _Pragma("unroll") for (int m = 0; m < 4; ++m) _Pragma("unroll") for (int k = 0; k < 2; ++k) dst[m][k] = *(const PG8_LAS bf16x8*)(lds + PG8_SA(b, h) + aoff + m * 2048 + k * 1024); } while (0)
; #define PG8_MMA(ai, bj, At, Bt) do { __builtin_amdgcn_s_setprio(1); _Pragma("unroll") for (int m = 0; m < 4; ++m) _Pragma("unroll") for (int n = 0; n < 2; ++n) _Pragma("unroll") for (int k = 0; k < 2; ++k) \
;         acc[ai][bj][m][n] = __builtin_amdgcn_mfma_f32_16x16x32_bf16(Bt[n][k], At[m][k], acc[ai][bj][m][n], 0, 0, 0); __builtin_amdgcn_s_setprio(0); } while (0)
; #define PG8_WAIT_V(n) asm volatile("s_waitcnt vmcnt(" #n ")" ::: "memory")
; #define PG8_WAIT_L(n) asm volatile("s_waitcnt lgkmcnt(" #n ")" ::: "memory")
; #define PG8_BAR __builtin_amdgcn_s_barrier()
; #define PG8_SCHED __builtin_amdgcn_sched_barrier(0)
; template <class Epi, class Sched, bool ALIGN_EPI = false, bool SP2 = false>
; __device__ __forceinline__ void gemm_phase(PG8_LAS unsigned char* lds, const Gemm g, const Sched& S, const Epi& E, const int tid) {
;     ...
;             PG8_WAIT_V(8); PG8_WAIT_L(0); PG8_BAR; PG8_MMA(0, 0, At, B0); PG8_MMA(0, 1, At, B1); PG8_BAR; PG8_SCHED;
;             PG8_LDA(At, 1, 1); PG8_STAGE(PG8_SB(1, 0), b3, voffB); PG8_STAGE(PG8_SB(1, 1), b3 + hstep, voffB); PG8_STAGE(PG8_SA(1, 0), a3, voffA);
;             PG8_WAIT_V(8); PG8_WAIT_L(0); PG8_BAR; PG8_MMA(1, 0, At, B0); PG8_MMA(1, 1, At, B1); PG8_BAR; PG8_SCHED;
	s_setprio 0
	s_add_i32 s38, s38, s75
	v_lshl_add_u64 v[194:195], v[246:247], 0, s[56:57]
	s_mov_b32 m0, s38
	ds_read_b128 v[214:217], v167 offset:49152
	ds_read_b128 v[218:221], v167 offset:50176
	ds_read_b128 v[222:225], v167 offset:51200
	ds_read_b128 v[226:229], v167 offset:52224
	ds_read_b128 v[230:233], v167 offset:53248
	ds_read_b128 v[234:237], v167 offset:54272
	ds_read_b128 v[238:241], v167 offset:55296
	ds_read_b128 v[242:245], v167 offset:56320
	global_load_lds_dwordx4 v[194:195], off
	s_add_i32 m0, s38, 0x2000
	s_add_u32 s50, s70, 0x40080
	v_lshl_add_u64 v[194:195], v[248:249], 0, s[56:57]
	s_addc_u32 s51, s71, 0
	s_add_i32 s38, s39, s75
	global_load_lds_dwordx4 v[194:195], off
	v_lshl_add_u64 v[194:195], s[50:51], 0, v[0:1]
	s_mov_b32 m0, s38
	s_nop 0
	global_load_lds_dwordx4 v[194:195], off
	v_lshl_add_u64 v[194:195], s[50:51], 0, v[130:131]
	s_add_i32 m0, s38, 0x2000
	s_nop 0
	global_load_lds_dwordx4 v[194:195], off
	v_lshl_add_u64 v[194:195], v[250:251], 0, s[56:57]
	s_mov_b32 m0, s80
	s_nop 0
	global_load_lds_dwordx4 v[194:195], off
	v_lshl_add_u64 v[194:195], v[252:253], 0, s[56:57]
	s_mov_b32 m0, s81
	s_nop 0
	global_load_lds_dwordx4 v[194:195], off
	s_waitcnt vmcnt(8)
	s_waitcnt lgkmcnt(0)
	s_setprio 1
	s_barrier
	v_mfma_f32_16x16x32_bf16 v[62:65], v[170:173], v[214:217], v[62:65]
	v_mfma_f32_16x16x32_bf16 v[58:61], v[178:181], v[214:217], v[58:61]
	v_mfma_f32_16x16x32_bf16 v[46:49], v[170:173], v[222:225], v[46:49]
	v_mfma_f32_16x16x32_bf16 v[42:45], v[178:181], v[222:225], v[42:45]
	v_mfma_f32_16x16x32_bf16 v[30:33], v[170:173], v[230:233], v[30:33]
	v_mfma_f32_16x16x32_bf16 v[26:29], v[178:181], v[230:233], v[26:29]
	v_mfma_f32_16x16x32_bf16 v[14:17], v[170:173], v[238:241], v[14:17]
	v_mfma_f32_16x16x32_bf16 v[10:13], v[178:181], v[238:241], v[10:13]
	v_mfma_f32_16x16x32_bf16 v[62:65], v[174:177], v[218:221], v[62:65]
	v_mfma_f32_16x16x32_bf16 v[58:61], v[182:185], v[218:221], v[58:61]
	v_mfma_f32_16x16x32_bf16 v[46:49], v[174:177], v[226:229], v[46:49]
	v_mfma_f32_16x16x32_bf16 v[42:45], v[182:185], v[226:229], v[42:45]
	v_mfma_f32_16x16x32_bf16 v[30:33], v[174:177], v[234:237], v[30:33]
	v_mfma_f32_16x16x32_bf16 v[26:29], v[182:185], v[234:237], v[26:29]
	v_mfma_f32_16x16x32_bf16 v[14:17], v[174:177], v[242:245], v[14:17]
	v_mfma_f32_16x16x32_bf16 v[10:13], v[182:185], v[242:245], v[10:13]
	v_mfma_f32_16x16x32_bf16 v[54:57], v[186:189], v[214:217], v[54:57]
	v_mfma_f32_16x16x32_bf16 v[50:53], v[206:209], v[214:217], v[50:53]
	v_mfma_f32_16x16x32_bf16 v[38:41], v[186:189], v[222:225], v[38:41]
	v_mfma_f32_16x16x32_bf16 v[34:37], v[206:209], v[222:225], v[34:37]
	v_mfma_f32_16x16x32_bf16 v[22:25], v[186:189], v[230:233], v[22:25]
	v_mfma_f32_16x16x32_bf16 v[18:21], v[206:209], v[230:233], v[18:21]
	v_mfma_f32_16x16x32_bf16 v[6:9], v[186:189], v[238:241], v[6:9]
	v_mfma_f32_16x16x32_bf16 v[2:5], v[206:209], v[238:241], v[2:5]
	v_mfma_f32_16x16x32_bf16 v[54:57], v[190:193], v[218:221], v[54:57]
	v_mfma_f32_16x16x32_bf16 v[50:53], v[210:213], v[218:221], v[50:53]
	v_mfma_f32_16x16x32_bf16 v[38:41], v[190:193], v[226:229], v[38:41]
	v_mfma_f32_16x16x32_bf16 v[34:37], v[210:213], v[226:229], v[34:37]
	v_mfma_f32_16x16x32_bf16 v[22:25], v[190:193], v[234:237], v[22:25]
	v_mfma_f32_16x16x32_bf16 v[18:21], v[210:213], v[234:237], v[18:21]
	v_mfma_f32_16x16x32_bf16 v[6:9], v[190:193], v[242:245], v[6:9]
	v_mfma_f32_16x16x32_bf16 v[2:5], v[210:213], v[242:245], v[2:5]
	s_barrier
	s_setprio 0
	s_add_i32 s91, s91, 2
	s_add_u32 s68, s68, 0x100
	s_addc_u32 s69, s69, 0
	s_cmp_gt_u32 s91, 13
	s_cbranch_scc1 .LBB0_90

; #define PG8_STAGE(bufoff, gbase, voff) do { _Pragma("unroll") for (int _i = 0; _i < 2; ++_i) \
;         __builtin_amdgcn_global_load_lds((const unsigned*)((const char*)(gbase) + (voff)[_i]), (PG8_LAS unsigned*)(lds + (bufoff) + ldsw + _i * 8192), 16, 0, 0); } while (0)
; #define PG8_LDA(dst, b, h) do { _Pragma("unroll") for (int m = 0; m < 4; ++m) _Pragma("unroll") for (int k = 0; k < 2; ++k) dst[m][k] = *(const PG8_LAS bf16x8*)(lds + PG8_SA(b, h) + aoff + m * 2048 + k * 1024); } while (0)
; #define PG8_LDB(dst, b, h) do { _Pragma("unroll") for (int n = 0; n < 2; ++n) _Pragma("unroll") for (int k = 0; k < 2; ++k) dst[n][k] = *(const PG8_LAS bf16x8*)(lds + PG8_SB(b, h) + boff + n * 2048 + k * 1024); } while (0)
; #define PG8_MMA(ai, bj, At, Bt) do { __builtin_amdgcn_s_setprio(1); _Pragma("unroll") for (int m = 0; m < 4; ++m) _Pragma("unroll") for (int n = 0; n < 2; ++n) _Pragma("unroll") for (int k = 0; k < 2; ++k) \
;         acc[ai][bj][m][n] = __builtin_amdgcn_mfma_f32_16x16x32_bf16(Bt[n][k], At[m][k], acc[ai][bj][m][n], 0, 0, 0); __builtin_amdgcn_s_setprio(0); } while (0)
; #define PG8_WAIT_V(n) asm volatile("s_waitcnt vmcnt(" #n ")" ::: "memory")
; #define PG8_WAIT_L(n) asm volatile("s_waitcnt lgkmcnt(" #n ")" ::: "memory")
; #define PG8_BAR __builtin_amdgcn_s_barrier()
; #define PG8_SCHED __builtin_amdgcn_sched_barrier(0)
; template <class Epi, class Sched, bool ALIGN_EPI = false, bool SP2 = false>
; __device__ __forceinline__ void gemm_phase(PG8_LAS unsigned char* lds, const Gemm g, const Sched& S, const Epi& E, const int tid) {
;     ...
;             const char* a2 = last ? nA : cA + (size_t)(t + 2) * kstep; const char* b2 = last ? nB : cB + (size_t)(t + 2) * kstep;
;             const char* a3 = a2 + kstep; const char* b3 = b2 + kstep;
;             if (last && has_next) S.a_ready(nxt);
;             if constexpr (SP2) {
;             PG8_LDB(B0, 0, 0); PG8_LDB(B1, 0, 1); PG8_SCHED; PG8_LDA(At, 0, 0); PG8_STAGE(PG8_SA(1, 1), a1 + hstep, voffA);
;             PG8_WAIT_V(8); PG8_WAIT_L(0); PG8_BAR; PG8_MMA(0, 0, At, B0); PG8_MMA(0, 1, At, B1); PG8_BAR; PG8_SCHED;
;             PG8_LDA(At, 0, 1); PG8_STAGE(PG8_SB(0, 0), b2, voffB); PG8_STAGE(PG8_SB(0, 1), b2 + hstep, voffB); PG8_STAGE(PG8_SA(0, 0), a2, voffA);
;             PG8_WAIT_V(8); PG8_WAIT_L(0); PG8_BAR; PG8_MMA(1, 0, At, B0); PG8_MMA(1, 1, At, B1); PG8_BAR; PG8_SCHED;
.LBB0_208:
	s_add_u32 s38, s10, s12
	s_addc_u32 s39, s11, s13
	s_add_u32 s38, s38, 0x100
	s_addc_u32 s39, s39, 0
	s_add_u32 s51, vcc_lo, s12
	s_addc_u32 s74, vcc_hi, s13
	s_add_i32 s59, 0, 0x10000
	s_cmpk_eq_i32 s12, 0x700
	s_cselect_b32 s77, s49, s39
	s_cselect_b32 s76, s78, s38
	v_add_u32_e32 v0, s59, v153
	s_cselect_b32 s75, s69, s74
	s_cselect_b32 s74, s79, s51
	s_add_i32 s51, 0, 0x14000
	ds_read_b128 v[170:173], v0
	ds_read_b128 v[174:177], v0 offset:1024
	ds_read_b128 v[178:181], v0 offset:2048
	ds_read_b128 v[182:185], v0 offset:3072
	v_add_u32_e32 v0, s51, v153
	ds_read_b128 v[186:189], v0
	ds_read_b128 v[190:193], v0 offset:1024
	ds_read_b128 v[206:209], v0 offset:2048
	ds_read_b128 v[210:213], v0 offset:3072
	v_lshl_add_u64 v[194:195], v[148:149], 0, s[12:13]
	s_add_i32 m0, s84, 0xc000
	ds_read_b128 v[214:217], v167
	ds_read_b128 v[218:221], v167 offset:1024
	ds_read_b128 v[222:225], v167 offset:2048
	ds_read_b128 v[226:229], v167 offset:3072
	ds_read_b128 v[230:233], v167 offset:4096
	ds_read_b128 v[234:237], v167 offset:5120
	ds_read_b128 v[238:241], v167 offset:6144
	ds_read_b128 v[242:245], v167 offset:7168
	global_load_lds_dwordx4 v[194:195], off
	v_lshl_add_u64 v[194:195], v[150:151], 0, s[12:13]
	s_add_i32 m0, s84, 0xe000
	s_nop 0
	global_load_lds_dwordx4 v[194:195], off
	s_waitcnt vmcnt(8)
	s_waitcnt lgkmcnt(0)
	s_setprio 1
	s_barrier
	v_mfma_f32_16x16x32_bf16 v[126:129], v[170:173], v[214:217], v[126:129]
	v_mfma_f32_16x16x32_bf16 v[122:125], v[178:181], v[214:217], v[122:125]
	v_mfma_f32_16x16x32_bf16 v[110:113], v[170:173], v[222:225], v[110:113]
	v_mfma_f32_16x16x32_bf16 v[106:109], v[178:181], v[222:225], v[106:109]
	v_mfma_f32_16x16x32_bf16 v[94:97], v[170:173], v[230:233], v[94:97]
	v_mfma_f32_16x16x32_bf16 v[90:93], v[178:181], v[230:233], v[90:93]
	v_mfma_f32_16x16x32_bf16 v[78:81], v[170:173], v[238:241], v[78:81]
	v_mfma_f32_16x16x32_bf16 v[74:77], v[178:181], v[238:241], v[74:77]
	v_mfma_f32_16x16x32_bf16 v[126:129], v[174:177], v[218:221], v[126:129]
	v_mfma_f32_16x16x32_bf16 v[122:125], v[182:185], v[218:221], v[122:125]
	v_mfma_f32_16x16x32_bf16 v[110:113], v[174:177], v[226:229], v[110:113]
	v_mfma_f32_16x16x32_bf16 v[106:109], v[182:185], v[226:229], v[106:109]
	v_mfma_f32_16x16x32_bf16 v[94:97], v[174:177], v[234:237], v[94:97]
	v_mfma_f32_16x16x32_bf16 v[90:93], v[182:185], v[234:237], v[90:93]
	v_mfma_f32_16x16x32_bf16 v[78:81], v[174:177], v[242:245], v[78:81]
	v_mfma_f32_16x16x32_bf16 v[74:77], v[182:185], v[242:245], v[74:77]
	v_mfma_f32_16x16x32_bf16 v[118:121], v[186:189], v[214:217], v[118:121]
	v_mfma_f32_16x16x32_bf16 v[114:117], v[206:209], v[214:217], v[114:117]
	v_mfma_f32_16x16x32_bf16 v[102:105], v[186:189], v[222:225], v[102:105]
	v_mfma_f32_16x16x32_bf16 v[98:101], v[206:209], v[222:225], v[98:101]
	v_mfma_f32_16x16x32_bf16 v[86:89], v[186:189], v[230:233], v[86:89]
	v_mfma_f32_16x16x32_bf16 v[82:85], v[206:209], v[230:233], v[82:85]
	v_mfma_f32_16x16x32_bf16 v[70:73], v[186:189], v[238:241], v[70:73]
	v_mfma_f32_16x16x32_bf16 v[66:69], v[206:209], v[238:241], v[66:69]
	v_mfma_f32_16x16x32_bf16 v[118:121], v[190:193], v[218:221], v[118:121]
	v_mfma_f32_16x16x32_bf16 v[114:117], v[210:213], v[218:221], v[114:117]
	v_mfma_f32_16x16x32_bf16 v[102:105], v[190:193], v[226:229], v[102:105]
	v_mfma_f32_16x16x32_bf16 v[98:101], v[210:213], v[226:229], v[98:101]
	v_mfma_f32_16x16x32_bf16 v[86:89], v[190:193], v[234:237], v[86:89]
	v_mfma_f32_16x16x32_bf16 v[82:85], v[210:213], v[234:237], v[82:85]
	v_mfma_f32_16x16x32_bf16 v[70:73], v[190:193], v[242:245], v[70:73]
	v_mfma_f32_16x16x32_bf16 v[66:69], v[210:213], v[242:245], v[66:69]
	s_barrier
	s_setprio 0
	s_add_i32 s38, s59, s83
	v_lshl_add_u64 v[194:195], s[74:75], 0, v[134:135]
	s_mov_b32 m0, s38
	ds_read_b128 v[214:217], v167 offset:16384
	ds_read_b128 v[218:221], v167 offset:17408
	ds_read_b128 v[222:225], v167 offset:18432
	ds_read_b128 v[226:229], v167 offset:19456
	ds_read_b128 v[230:233], v167 offset:20480
	ds_read_b128 v[234:237], v167 offset:21504
	ds_read_b128 v[238:241], v167 offset:22528
	ds_read_b128 v[242:245], v167 offset:23552
	global_load_lds_dwordx4 v[194:195], off
	s_add_i32 m0, s38, 0x2000
	s_add_u32 s38, s74, 0x40000
	v_lshl_add_u64 v[246:247], s[74:75], 0, v[130:131]
	s_addc_u32 s39, s75, 0
	s_add_i32 s51, s51, s83
	global_load_lds_dwordx4 v[246:247], off
	v_lshl_add_u64 v[248:249], s[38:39], 0, v[134:135]
	s_mov_b32 m0, s51
	v_lshl_add_u64 v[250:251], s[76:77], 0, v[132:133]
	global_load_lds_dwordx4 v[248:249], off
	v_lshl_add_u64 v[248:249], s[38:39], 0, v[130:131]
	s_add_i32 m0, s51, 0x2000
	s_nop 0
	global_load_lds_dwordx4 v[248:249], off
	v_lshl_add_u64 v[248:249], s[76:77], 0, v[136:137]
	s_mov_b32 m0, s84
	s_nop 0
	global_load_lds_dwordx4 v[248:249], off
	s_mov_b32 m0, s85
	s_nop 0
	global_load_lds_dwordx4 v[250:251], off
	s_waitcnt vmcnt(8)
	s_waitcnt lgkmcnt(0)
	s_setprio 1
	s_barrier
; #define PG8_STAGE(bufoff, gbase, voff) do { _Pragma("unroll") for (int _i = 0; _i < 2; ++_i) \
;         __builtin_amdgcn_global_load_lds((const unsigned*)((const char*)(gbase) + (voff)[_i]), (PG8_LAS unsigned*)(lds + (bufoff) + ldsw + _i * 8192), 16, 0, 0); } while (0)
; #define PG8_LDA(dst, b, h) do { _Pragma("unroll") for (int m = 0; m < 4; ++m) _Pragma("unroll") for (int k = 0; k < 2; ++k) dst[m][k] = *(const PG8_LAS bf16x8*)(lds + PG8_SA(b, h) + aoff + m * 2048 + k * 1024); } while (0)
; #define PG8_LDB(dst, b, h) do { _Pragma("unroll") for (int n = 0; n < 2; ++n) _Pragma("unroll") for (int k = 0; k < 2; ++k) dst[n][k] = *(const PG8_LAS bf16x8*)(lds + PG8_SB(b, h) + boff + n * 2048 + k * 1024); } while (0)
; #define PG8_MMA(ai, bj, At, Bt) do { __builtin_amdgcn_s_setprio(1); _Pragma("unroll") for (int m = 0; m < 4; ++m) _Pragma("unroll") for (int n = 0; n < 2; ++n) _Pragma("unroll") for (int k = 0; k < 2; ++k) \
;         acc[ai][bj][m][n] = __builtin_amdgcn_mfma_f32_16x16x32_bf16(Bt[n][k], At[m][k], acc[ai][bj][m][n], 0, 0, 0); __builtin_amdgcn_s_setprio(0); } while (0)
; #define PG8_WAIT_V(n) asm volatile("s_waitcnt vmcnt(" #n ")" ::: "memory")
; #define PG8_WAIT_L(n) asm volatile("s_waitcnt lgkmcnt(" #n ")" ::: "memory")
; #define PG8_BAR __builtin_amdgcn_s_barrier()
; #define PG8_SCHED __builtin_amdgcn_sched_barrier(0)
; template <class Epi, class Sched, bool ALIGN_EPI = false, bool SP2 = false>
; __device__ __forceinline__ void gemm_phase(PG8_LAS unsigned char* lds, const Gemm g, const Sched& S, const Epi& E, const int tid) {
;     ...
;             PG8_WAIT_V(8); PG8_WAIT_L(0); PG8_BAR; PG8_MMA(1, 0, At, B0); PG8_MMA(1, 1, At, B1); PG8_BAR; PG8_SCHED;
;             PG8_LDB(B0, 1, 0); PG8_LDB(B1, 1, 1); PG8_SCHED; PG8_LDA(At, 1, 0); PG8_STAGE(PG8_SA(0, 1), a2 + hstep, voffA);
;             PG8_WAIT_V(8); PG8_WAIT_L(0); PG8_BAR; PG8_MMA(0, 0, At, B0); PG8_MMA(0, 1, At, B1); PG8_BAR; PG8_SCHED;
	v_mfma_f32_16x16x32_bf16 v[62:65], v[170:173], v[214:217], v[62:65]
	v_mfma_f32_16x16x32_bf16 v[58:61], v[178:181], v[214:217], v[58:61]
	v_mfma_f32_16x16x32_bf16 v[46:49], v[170:173], v[222:225], v[46:49]
	v_mfma_f32_16x16x32_bf16 v[42:45], v[178:181], v[222:225], v[42:45]
	v_mfma_f32_16x16x32_bf16 v[30:33], v[170:173], v[230:233], v[30:33]
	v_mfma_f32_16x16x32_bf16 v[26:29], v[178:181], v[230:233], v[26:29]
	v_mfma_f32_16x16x32_bf16 v[14:17], v[170:173], v[238:241], v[14:17]
	v_mfma_f32_16x16x32_bf16 v[10:13], v[178:181], v[238:241], v[10:13]
	v_mfma_f32_16x16x32_bf16 v[62:65], v[174:177], v[218:221], v[62:65]
	v_mfma_f32_16x16x32_bf16 v[58:61], v[182:185], v[218:221], v[58:61]
	v_mfma_f32_16x16x32_bf16 v[46:49], v[174:177], v[226:229], v[46:49]
	v_mfma_f32_16x16x32_bf16 v[42:45], v[182:185], v[226:229], v[42:45]
	v_mfma_f32_16x16x32_bf16 v[30:33], v[174:177], v[234:237], v[30:33]
	v_mfma_f32_16x16x32_bf16 v[26:29], v[182:185], v[234:237], v[26:29]
	v_mfma_f32_16x16x32_bf16 v[14:17], v[174:177], v[242:245], v[14:17]
	v_mfma_f32_16x16x32_bf16 v[10:13], v[182:185], v[242:245], v[10:13]
	v_mfma_f32_16x16x32_bf16 v[54:57], v[186:189], v[214:217], v[54:57]
	v_mfma_f32_16x16x32_bf16 v[50:53], v[206:209], v[214:217], v[50:53]
	v_mfma_f32_16x16x32_bf16 v[38:41], v[186:189], v[222:225], v[38:41]
	v_mfma_f32_16x16x32_bf16 v[34:37], v[206:209], v[222:225], v[34:37]
	v_mfma_f32_16x16x32_bf16 v[22:25], v[186:189], v[230:233], v[22:25]
	v_mfma_f32_16x16x32_bf16 v[18:21], v[206:209], v[230:233], v[18:21]
	v_mfma_f32_16x16x32_bf16 v[6:9], v[186:189], v[238:241], v[6:9]
	v_mfma_f32_16x16x32_bf16 v[2:5], v[206:209], v[238:241], v[2:5]
	v_mfma_f32_16x16x32_bf16 v[54:57], v[190:193], v[218:221], v[54:57]
	v_mfma_f32_16x16x32_bf16 v[50:53], v[210:213], v[218:221], v[50:53]
	v_mfma_f32_16x16x32_bf16 v[38:41], v[190:193], v[226:229], v[38:41]
	v_mfma_f32_16x16x32_bf16 v[34:37], v[210:213], v[226:229], v[34:37]
	v_mfma_f32_16x16x32_bf16 v[22:25], v[190:193], v[234:237], v[22:25]
	v_mfma_f32_16x16x32_bf16 v[18:21], v[210:213], v[234:237], v[18:21]
	v_mfma_f32_16x16x32_bf16 v[6:9], v[190:193], v[242:245], v[6:9]
	v_mfma_f32_16x16x32_bf16 v[2:5], v[210:213], v[242:245], v[2:5]
	s_barrier
	s_setprio 0
	s_add_i32 s51, 0, 0x18000
	v_add_u32_e32 v0, s51, v153
	s_add_i32 s59, 0, 0x1c000
	ds_read_b128 v[170:173], v0
	ds_read_b128 v[174:177], v0 offset:1024
	ds_read_b128 v[178:181], v0 offset:2048
	ds_read_b128 v[182:185], v0 offset:3072
	v_add_u32_e32 v0, s59, v153
	ds_read_b128 v[186:189], v0
	ds_read_b128 v[190:193], v0 offset:1024
	ds_read_b128 v[206:209], v0 offset:2048
	ds_read_b128 v[210:213], v0 offset:3072
	s_add_u32 s38, s76, 0x40000
	s_addc_u32 s39, s77, 0
	s_mov_b32 m0, s86
	v_lshl_add_u64 v[252:253], s[38:39], 0, v[136:137]
	ds_read_b128 v[214:217], v167 offset:32768
	ds_read_b128 v[218:221], v167 offset:33792
	ds_read_b128 v[222:225], v167 offset:34816
	ds_read_b128 v[226:229], v167 offset:35840
	ds_read_b128 v[230:233], v167 offset:36864
	ds_read_b128 v[234:237], v167 offset:37888
	ds_read_b128 v[238:241], v167 offset:38912
	ds_read_b128 v[242:245], v167 offset:39936
	global_load_lds_dwordx4 v[252:253], off
	v_lshl_add_u64 v[252:253], s[38:39], 0, v[132:133]
	s_mov_b32 m0, s87
	s_nop 0
	global_load_lds_dwordx4 v[252:253], off
	s_waitcnt vmcnt(8)
	s_waitcnt lgkmcnt(0)
	s_setprio 1
	s_barrier
	v_mfma_f32_16x16x32_bf16 v[126:129], v[170:173], v[214:217], v[126:129]
	v_mfma_f32_16x16x32_bf16 v[122:125], v[178:181], v[214:217], v[122:125]
	v_mfma_f32_16x16x32_bf16 v[110:113], v[170:173], v[222:225], v[110:113]
	v_mfma_f32_16x16x32_bf16 v[106:109], v[178:181], v[222:225], v[106:109]
	v_mfma_f32_16x16x32_bf16 v[94:97], v[170:173], v[230:233], v[94:97]
	v_mfma_f32_16x16x32_bf16 v[90:93], v[178:181], v[230:233], v[90:93]
	v_mfma_f32_16x16x32_bf16 v[78:81], v[170:173], v[238:241], v[78:81]
	v_mfma_f32_16x16x32_bf16 v[74:77], v[178:181], v[238:241], v[74:77]
	v_mfma_f32_16x16x32_bf16 v[126:129], v[174:177], v[218:221], v[126:129]
	v_mfma_f32_16x16x32_bf16 v[122:125], v[182:185], v[218:221], v[122:125]
	v_mfma_f32_16x16x32_bf16 v[110:113], v[174:177], v[226:229], v[110:113]
	v_mfma_f32_16x16x32_bf16 v[106:109], v[182:185], v[226:229], v[106:109]
	v_mfma_f32_16x16x32_bf16 v[94:97], v[174:177], v[234:237], v[94:97]
	v_mfma_f32_16x16x32_bf16 v[90:93], v[182:185], v[234:237], v[90:93]
	v_mfma_f32_16x16x32_bf16 v[78:81], v[174:177], v[242:245], v[78:81]
	v_mfma_f32_16x16x32_bf16 v[74:77], v[182:185], v[242:245], v[74:77]
	v_mfma_f32_16x16x32_bf16 v[118:121], v[186:189], v[214:217], v[118:121]
	v_mfma_f32_16x16x32_bf16 v[114:117], v[206:209], v[214:217], v[114:117]
	v_mfma_f32_16x16x32_bf16 v[102:105], v[186:189], v[222:225], v[102:105]
	v_mfma_f32_16x16x32_bf16 v[98:101], v[206:209], v[222:225], v[98:101]
	v_mfma_f32_16x16x32_bf16 v[86:89], v[186:189], v[230:233], v[86:89]
	v_mfma_f32_16x16x32_bf16 v[82:85], v[206:209], v[230:233], v[82:85]
	v_mfma_f32_16x16x32_bf16 v[70:73], v[186:189], v[238:241], v[70:73]
	v_mfma_f32_16x16x32_bf16 v[66:69], v[206:209], v[238:241], v[66:69]
	v_mfma_f32_16x16x32_bf16 v[118:121], v[190:193], v[218:221], v[118:121]
	v_mfma_f32_16x16x32_bf16 v[114:117], v[210:213], v[218:221], v[114:117]
	v_mfma_f32_16x16x32_bf16 v[102:105], v[190:193], v[226:229], v[102:105]
	v_mfma_f32_16x16x32_bf16 v[98:101], v[210:213], v[226:229], v[98:101]
	v_mfma_f32_16x16x32_bf16 v[86:89], v[190:193], v[234:237], v[86:89]
	v_mfma_f32_16x16x32_bf16 v[82:85], v[210:213], v[234:237], v[82:85]
	v_mfma_f32_16x16x32_bf16 v[70:73], v[190:193], v[242:245], v[70:73]
	v_mfma_f32_16x16x32_bf16 v[66:69], v[210:213], v[242:245], v[66:69]
	s_barrier
; #define PG8_STAGE(bufoff, gbase, voff) do { _Pragma("unroll") for (int _i = 0; _i < 2; ++_i) \
;         __builtin_amdgcn_global_load_lds((const unsigned*)((const char*)(gbase) + (voff)[_i]), (PG8_LAS unsigned*)(lds + (bufoff) + ldsw + _i * 8192), 16, 0, 0); } while (0)
; #define PG8_LDA(dst, b, h) do { _Pragma("unroll") for (int m = 0; m < 4; ++m) _Pragma("unroll") for (int k = 0; k < 2; ++k) dst[m][k] = *(const PG8_LAS bf16x8*)(lds + PG8_SA(b, h) + aoff + m * 2048 + k * 1024); } while (0)
; #define PG8_MMA(ai, bj, At, Bt) do { __builtin_amdgcn_s_setprio(1); _Pragma("unroll") for (int m = 0; m < 4; ++m) _Pragma("unroll") for (int n = 0; n < 2; ++n) _Pragma("unroll") for (int k = 0; k < 2; ++k) \
;         acc[ai][bj][m][n] = __builtin_amdgcn_mfma_f32_16x16x32_bf16(Bt[n][k], At[m][k], acc[ai][bj][m][n], 0, 0, 0); __builtin_amdgcn_s_setprio(0); } while (0)
; #define PG8_WAIT_V(n) asm volatile("s_waitcnt vmcnt(" #n ")" ::: "memory")
; #define PG8_WAIT_L(n) asm volatile("s_waitcnt lgkmcnt(" #n ")" ::: "memory")
; #define PG8_BAR __builtin_amdgcn_s_barrier()
; #define PG8_SCHED __builtin_amdgcn_sched_barrier(0)
; template <class Epi, class Sched, bool ALIGN_EPI = false, bool SP2 = false>
; __device__ __forceinline__ void gemm_phase(PG8_LAS unsigned char* lds, const Gemm g, const Sched& S, const Epi& E, const int tid) {
;     ...
;             PG8_WAIT_V(8); PG8_WAIT_L(0); PG8_BAR; PG8_MMA(0, 0, At, B0); PG8_MMA(0, 1, At, B1); PG8_BAR; PG8_SCHED;
;             PG8_LDA(At, 1, 1); PG8_STAGE(PG8_SB(1, 0), b3, voffB); PG8_STAGE(PG8_SB(1, 1), b3 + hstep, voffB); PG8_STAGE(PG8_SA(1, 0), a3, voffA);
;             PG8_WAIT_V(8); PG8_WAIT_L(0); PG8_BAR; PG8_MMA(1, 0, At, B0); PG8_MMA(1, 1, At, B1); PG8_BAR; PG8_SCHED;
	s_setprio 0
	s_add_i32 s38, s51, s83
	v_lshl_add_u64 v[194:195], v[194:195], 0, s[56:57]
	s_mov_b32 m0, s38
	ds_read_b128 v[214:217], v167 offset:49152
	ds_read_b128 v[218:221], v167 offset:50176
	ds_read_b128 v[222:225], v167 offset:51200
	ds_read_b128 v[226:229], v167 offset:52224
	ds_read_b128 v[230:233], v167 offset:53248
	ds_read_b128 v[234:237], v167 offset:54272
	ds_read_b128 v[238:241], v167 offset:55296
	ds_read_b128 v[242:245], v167 offset:56320
	global_load_lds_dwordx4 v[194:195], off
	s_add_i32 m0, s38, 0x2000
	s_add_u32 s38, s74, 0x40080
	v_lshl_add_u64 v[194:195], v[246:247], 0, s[56:57]
	s_addc_u32 s39, s75, 0
	s_add_i32 s51, s59, s83
	global_load_lds_dwordx4 v[194:195], off
	v_lshl_add_u64 v[194:195], s[38:39], 0, v[134:135]
	s_mov_b32 m0, s51
	s_nop 0
	global_load_lds_dwordx4 v[194:195], off
	v_lshl_add_u64 v[194:195], s[38:39], 0, v[130:131]
	s_add_i32 m0, s51, 0x2000
	s_nop 0
	global_load_lds_dwordx4 v[194:195], off
	v_lshl_add_u64 v[194:195], v[248:249], 0, s[56:57]
	s_mov_b32 m0, s88
	s_nop 0
	global_load_lds_dwordx4 v[194:195], off
	v_lshl_add_u64 v[194:195], v[250:251], 0, s[56:57]
	s_mov_b32 m0, s89
	s_nop 0
	global_load_lds_dwordx4 v[194:195], off
	s_waitcnt vmcnt(8)
	s_waitcnt lgkmcnt(0)
	s_setprio 1
	s_barrier
	v_mfma_f32_16x16x32_bf16 v[62:65], v[170:173], v[214:217], v[62:65]
	v_mfma_f32_16x16x32_bf16 v[58:61], v[178:181], v[214:217], v[58:61]
	v_mfma_f32_16x16x32_bf16 v[46:49], v[170:173], v[222:225], v[46:49]
	v_mfma_f32_16x16x32_bf16 v[42:45], v[178:181], v[222:225], v[42:45]
	v_mfma_f32_16x16x32_bf16 v[30:33], v[170:173], v[230:233], v[30:33]
	v_mfma_f32_16x16x32_bf16 v[26:29], v[178:181], v[230:233], v[26:29]
	v_mfma_f32_16x16x32_bf16 v[14:17], v[170:173], v[238:241], v[14:17]
	v_mfma_f32_16x16x32_bf16 v[10:13], v[178:181], v[238:241], v[10:13]
	v_mfma_f32_16x16x32_bf16 v[62:65], v[174:177], v[218:221], v[62:65]
	v_mfma_f32_16x16x32_bf16 v[58:61], v[182:185], v[218:221], v[58:61]
	v_mfma_f32_16x16x32_bf16 v[46:49], v[174:177], v[226:229], v[46:49]
	v_mfma_f32_16x16x32_bf16 v[42:45], v[182:185], v[226:229], v[42:45]
	v_mfma_f32_16x16x32_bf16 v[30:33], v[174:177], v[234:237], v[30:33]
	v_mfma_f32_16x16x32_bf16 v[26:29], v[182:185], v[234:237], v[26:29]
	v_mfma_f32_16x16x32_bf16 v[14:17], v[174:177], v[242:245], v[14:17]
	v_mfma_f32_16x16x32_bf16 v[10:13], v[182:185], v[242:245], v[10:13]
	v_mfma_f32_16x16x32_bf16 v[54:57], v[186:189], v[214:217], v[54:57]
	v_mfma_f32_16x16x32_bf16 v[50:53], v[206:209], v[214:217], v[50:53]
	v_mfma_f32_16x16x32_bf16 v[38:41], v[186:189], v[222:225], v[38:41]
	v_mfma_f32_16x16x32_bf16 v[34:37], v[206:209], v[222:225], v[34:37]
	v_mfma_f32_16x16x32_bf16 v[22:25], v[186:189], v[230:233], v[22:25]
	v_mfma_f32_16x16x32_bf16 v[18:21], v[206:209], v[230:233], v[18:21]
	v_mfma_f32_16x16x32_bf16 v[6:9], v[186:189], v[238:241], v[6:9]
	v_mfma_f32_16x16x32_bf16 v[2:5], v[206:209], v[238:241], v[2:5]
	v_mfma_f32_16x16x32_bf16 v[54:57], v[190:193], v[218:221], v[54:57]
	v_mfma_f32_16x16x32_bf16 v[50:53], v[210:213], v[218:221], v[50:53]
	v_mfma_f32_16x16x32_bf16 v[38:41], v[190:193], v[226:229], v[38:41]
	v_mfma_f32_16x16x32_bf16 v[34:37], v[210:213], v[226:229], v[34:37]
	v_mfma_f32_16x16x32_bf16 v[22:25], v[190:193], v[234:237], v[22:25]
	v_mfma_f32_16x16x32_bf16 v[18:21], v[210:213], v[234:237], v[18:21]
	v_mfma_f32_16x16x32_bf16 v[6:9], v[190:193], v[242:245], v[6:9]
	v_mfma_f32_16x16x32_bf16 v[2:5], v[210:213], v[242:245], v[2:5]
	s_barrier
	s_setprio 0
	s_add_i32 s50, s50, 2
	s_add_u32 s12, s12, 0x100
	s_addc_u32 s13, s13, 0
	s_cmp_gt_u32 s50, 13
	s_cbranch_scc1 .LBB0_211

; #define PG8_STAGE(bufoff, gbase, voff) do { _Pragma("unroll") for (int _i = 0; _i < 2; ++_i) \
;         __builtin_amdgcn_global_load_lds((const unsigned*)((const char*)(gbase) + (voff)[_i]), (PG8_LAS unsigned*)(lds + (bufoff) + ldsw + _i * 8192), 16, 0, 0); } while (0)
; #define PG8_LDA(dst, b, h) do { _Pragma("unroll") for (int m = 0; m < 4; ++m) _Pragma("unroll") for (int k = 0; k < 2; ++k) dst[m][k] = *(const PG8_LAS bf16x8*)(lds + PG8_SA(b, h) + aoff + m * 2048 + k * 1024); } while (0)
; #define PG8_LDB(dst, b, h) do { _Pragma("unroll") for (int n = 0; n < 2; ++n) _Pragma("unroll") for (int k = 0; k < 2; ++k) dst[n][k] = *(const PG8_LAS bf16x8*)(lds + PG8_SB(b, h) + boff + n * 2048 + k * 1024); } while (0)
; #define PG8_MMA(ai, bj, At, Bt) do { __builtin_amdgcn_s_setprio(1); _Pragma("unroll") for (int m = 0; m < 4; ++m) _Pragma("unroll") for (int n = 0; n < 2; ++n) _Pragma("unroll") for (int k = 0; k < 2; ++k) \
;         acc[ai][bj][m][n] = __builtin_amdgcn_mfma_f32_16x16x32_bf16(Bt[n][k], At[m][k], acc[ai][bj][m][n], 0, 0, 0); __builtin_amdgcn_s_setprio(0); } while (0)
; #define PG8_WAIT_V(n) asm volatile("s_waitcnt vmcnt(" #n ")" ::: "memory")
; #define PG8_WAIT_L(n) asm volatile("s_waitcnt lgkmcnt(" #n ")" ::: "memory")
; #define PG8_BAR __builtin_amdgcn_s_barrier()
; #define PG8_SCHED __builtin_amdgcn_sched_barrier(0)
; template <class Epi, class Sched, bool ALIGN_EPI = false, bool SP2 = false>
; __device__ __forceinline__ void gemm_phase(PG8_LAS unsigned char* lds, const Gemm g, const Sched& S, const Epi& E, const int tid) {
;     ...
;             const char* a2 = last ? nA : cA + (size_t)(t + 2) * kstep; const char* b2 = last ? nB : cB + (size_t)(t + 2) * kstep;
;             const char* a3 = a2 + kstep; const char* b3 = b2 + kstep;
;             if (last && has_next) S.a_ready(nxt);
;             if constexpr (SP2) {
;             PG8_LDB(B0, 0, 0); PG8_LDB(B1, 0, 1); PG8_SCHED; PG8_LDA(At, 0, 0); PG8_STAGE(PG8_SA(1, 1), a1 + hstep, voffA);
;             PG8_WAIT_V(8); PG8_WAIT_L(0); PG8_BAR; PG8_MMA(0, 0, At, B0); PG8_MMA(0, 1, At, B1); PG8_BAR; PG8_SCHED;
;             PG8_LDA(At, 0, 1); PG8_STAGE(PG8_SB(0, 0), b2, voffB); PG8_STAGE(PG8_SB(0, 1), b2 + hstep, voffB); PG8_STAGE(PG8_SA(0, 0), a2, voffA);
;             PG8_WAIT_V(8); PG8_WAIT_L(0); PG8_BAR; PG8_MMA(1, 0, At, B0); PG8_MMA(1, 1, At, B1); PG8_BAR; PG8_SCHED;
.LBB0_618:
	s_add_i32 s85, s70, 2
	s_add_u32 s38, s68, 0x80
	s_addc_u32 s39, s69, 0
	s_add_i32 s59, 0, 0x10000
	s_cmp_eq_u32 s81, s70
	s_cselect_b32 s71, s11, s39
	s_cselect_b32 s70, s10, s38
	s_cselect_b32 s39, s67, s51
	s_cselect_b32 s38, s66, s50
	s_add_i32 s86, 0, 0x14000
	v_add_u32_e32 v142, s59, v205
	v_add_u32_e32 v180, s86, v205
	ds_read_b128 v[130:133], v142
	ds_read_b128 v[134:137], v142 offset:1024
	ds_read_b128 v[138:141], v142 offset:2048
	ds_read_b128 v[142:145], v142 offset:3072
	ds_read_b128 v[146:149], v180
	ds_read_b128 v[150:153], v180 offset:1024
	ds_read_b128 v[176:179], v180 offset:2048
	ds_read_b128 v[180:183], v180 offset:3072
	v_lshl_add_u64 v[192:193], s[68:69], 0, v[172:173]
	s_add_i32 m0, s73, 0xc000
	ds_read_b128 v[184:187], v207
	ds_read_b128 v[188:191], v207 offset:1024
	ds_read_b128 v[208:211], v207 offset:2048
	ds_read_b128 v[212:215], v207 offset:3072
	ds_read_b128 v[216:219], v207 offset:4096
	ds_read_b128 v[220:223], v207 offset:5120
	ds_read_b128 v[224:227], v207 offset:6144
	ds_read_b128 v[228:231], v207 offset:7168
	global_load_lds_dwordx4 v[192:193], off
	v_lshl_add_u64 v[192:193], s[68:69], 0, v[174:175]
	s_add_i32 m0, s73, 0xe000
	s_nop 0
	global_load_lds_dwordx4 v[192:193], off
	s_waitcnt vmcnt(8)
	s_waitcnt lgkmcnt(0)
	s_setprio 1
	s_barrier
	v_mfma_f32_16x16x32_bf16 v[126:129], v[130:133], v[184:187], v[126:129]
	v_mfma_f32_16x16x32_bf16 v[122:125], v[138:141], v[184:187], v[122:125]
	v_mfma_f32_16x16x32_bf16 v[110:113], v[130:133], v[208:211], v[110:113]
	v_mfma_f32_16x16x32_bf16 v[106:109], v[138:141], v[208:211], v[106:109]
	v_mfma_f32_16x16x32_bf16 v[94:97], v[130:133], v[216:219], v[94:97]
	v_mfma_f32_16x16x32_bf16 v[90:93], v[138:141], v[216:219], v[90:93]
	v_mfma_f32_16x16x32_bf16 v[78:81], v[130:133], v[224:227], v[78:81]
	v_mfma_f32_16x16x32_bf16 v[74:77], v[138:141], v[224:227], v[74:77]
	v_mfma_f32_16x16x32_bf16 v[126:129], v[134:137], v[188:191], v[126:129]
	v_mfma_f32_16x16x32_bf16 v[122:125], v[142:145], v[188:191], v[122:125]
	v_mfma_f32_16x16x32_bf16 v[110:113], v[134:137], v[212:215], v[110:113]
	v_mfma_f32_16x16x32_bf16 v[106:109], v[142:145], v[212:215], v[106:109]
	v_mfma_f32_16x16x32_bf16 v[94:97], v[134:137], v[220:223], v[94:97]
	v_mfma_f32_16x16x32_bf16 v[90:93], v[142:145], v[220:223], v[90:93]
	v_mfma_f32_16x16x32_bf16 v[78:81], v[134:137], v[228:231], v[78:81]
	v_mfma_f32_16x16x32_bf16 v[74:77], v[142:145], v[228:231], v[74:77]
	v_mfma_f32_16x16x32_bf16 v[118:121], v[146:149], v[184:187], v[118:121]
	v_mfma_f32_16x16x32_bf16 v[114:117], v[176:179], v[184:187], v[114:117]
	v_mfma_f32_16x16x32_bf16 v[102:105], v[146:149], v[208:211], v[102:105]
	v_mfma_f32_16x16x32_bf16 v[98:101], v[176:179], v[208:211], v[98:101]
	v_mfma_f32_16x16x32_bf16 v[86:89], v[146:149], v[216:219], v[86:89]
	v_mfma_f32_16x16x32_bf16 v[82:85], v[176:179], v[216:219], v[82:85]
	v_mfma_f32_16x16x32_bf16 v[70:73], v[146:149], v[224:227], v[70:73]
	v_mfma_f32_16x16x32_bf16 v[66:69], v[176:179], v[224:227], v[66:69]
	v_mfma_f32_16x16x32_bf16 v[118:121], v[150:153], v[188:191], v[118:121]
	v_mfma_f32_16x16x32_bf16 v[114:117], v[180:183], v[188:191], v[114:117]
	v_mfma_f32_16x16x32_bf16 v[102:105], v[150:153], v[212:215], v[102:105]
	v_mfma_f32_16x16x32_bf16 v[98:101], v[180:183], v[212:215], v[98:101]
	v_mfma_f32_16x16x32_bf16 v[86:89], v[150:153], v[220:223], v[86:89]
	v_mfma_f32_16x16x32_bf16 v[82:85], v[180:183], v[220:223], v[82:85]
	v_mfma_f32_16x16x32_bf16 v[70:73], v[150:153], v[228:231], v[70:73]
	v_mfma_f32_16x16x32_bf16 v[66:69], v[180:183], v[228:231], v[66:69]
	s_barrier
	s_setprio 0
	s_add_i32 s59, s59, s72
	v_lshl_add_u64 v[192:193], s[38:39], 0, v[0:1]
	s_mov_b32 m0, s59
	ds_read_b128 v[184:187], v207 offset:16384
	ds_read_b128 v[188:191], v207 offset:17408
	ds_read_b128 v[208:211], v207 offset:18432
	ds_read_b128 v[212:215], v207 offset:19456
	ds_read_b128 v[216:219], v207 offset:20480
	ds_read_b128 v[220:223], v207 offset:21504
	ds_read_b128 v[224:227], v207 offset:22528
	ds_read_b128 v[228:231], v207 offset:23552
	global_load_lds_dwordx4 v[192:193], off
	s_add_i32 m0, s59, 0x2000
	v_lshl_add_u64 v[194:195], s[38:39], 0, v[166:167]
	s_add_u32 s38, s38, s14
	s_addc_u32 s39, s39, 0
	s_add_i32 s59, s86, s72
	global_load_lds_dwordx4 v[194:195], off
	v_lshl_add_u64 v[232:233], s[38:39], 0, v[0:1]
	s_mov_b32 m0, s59
	v_lshl_add_u64 v[234:235], s[38:39], 0, v[166:167]
	global_load_lds_dwordx4 v[232:233], off
	s_add_i32 m0, s59, 0x2000
	v_lshl_add_u64 v[236:237], s[70:71], 0, v[170:171]
	global_load_lds_dwordx4 v[234:235], off
	s_mov_b32 m0, s73
	v_lshl_add_u64 v[238:239], s[70:71], 0, v[168:169]
	global_load_lds_dwordx4 v[236:237], off
	s_mov_b32 m0, s74
	s_nop 0
	global_load_lds_dwordx4 v[238:239], off
	s_waitcnt vmcnt(8)
	s_waitcnt lgkmcnt(0)
	s_setprio 1
	s_barrier
; #define PG8_STAGE(bufoff, gbase, voff) do { _Pragma("unroll") for (int _i = 0; _i < 2; ++_i) \
;         __builtin_amdgcn_global_load_lds((const unsigned*)((const char*)(gbase) + (voff)[_i]), (PG8_LAS unsigned*)(lds + (bufoff) + ldsw + _i * 8192), 16, 0, 0); } while (0)
; #define PG8_LDA(dst, b, h) do { _Pragma("unroll") for (int m = 0; m < 4; ++m) _Pragma("unroll") for (int k = 0; k < 2; ++k) dst[m][k] = *(const PG8_LAS bf16x8*)(lds + PG8_SA(b, h) + aoff + m * 2048 + k * 1024); } while (0)
; #define PG8_LDB(dst, b, h) do { _Pragma("unroll") for (int n = 0; n < 2; ++n) _Pragma("unroll") for (int k = 0; k < 2; ++k) dst[n][k] = *(const PG8_LAS bf16x8*)(lds + PG8_SB(b, h) + boff + n * 2048 + k * 1024); } while (0)
; #define PG8_MMA(ai, bj, At, Bt) do { __builtin_amdgcn_s_setprio(1); _Pragma("unroll") for (int m = 0; m < 4; ++m) _Pragma("unroll") for (int n = 0; n < 2; ++n) _Pragma("unroll") for (int k = 0; k < 2; ++k) \
;         acc[ai][bj][m][n] = __builtin_amdgcn_mfma_f32_16x16x32_bf16(Bt[n][k], At[m][k], acc[ai][bj][m][n], 0, 0, 0); __builtin_amdgcn_s_setprio(0); } while (0)
; #define PG8_WAIT_V(n) asm volatile("s_waitcnt vmcnt(" #n ")" ::: "memory")
; #define PG8_WAIT_L(n) asm volatile("s_waitcnt lgkmcnt(" #n ")" ::: "memory")
; #define PG8_BAR __builtin_amdgcn_s_barrier()
; #define PG8_SCHED __builtin_amdgcn_sched_barrier(0)
; template <class Epi, class Sched, bool ALIGN_EPI = false, bool SP2 = false>
; __device__ __forceinline__ void gemm_phase(PG8_LAS unsigned char* lds, const Gemm g, const Sched& S, const Epi& E, const int tid) {
;     ...
;             PG8_WAIT_V(8); PG8_WAIT_L(0); PG8_BAR; PG8_MMA(1, 0, At, B0); PG8_MMA(1, 1, At, B1); PG8_BAR; PG8_SCHED;
;             PG8_LDB(B0, 1, 0); PG8_LDB(B1, 1, 1); PG8_SCHED; PG8_LDA(At, 1, 0); PG8_STAGE(PG8_SA(0, 1), a2 + hstep, voffA);
;             PG8_WAIT_V(8); PG8_WAIT_L(0); PG8_BAR; PG8_MMA(0, 0, At, B0); PG8_MMA(0, 1, At, B1); PG8_BAR; PG8_SCHED;
	v_mfma_f32_16x16x32_bf16 v[62:65], v[130:133], v[184:187], v[62:65]
	v_mfma_f32_16x16x32_bf16 v[58:61], v[138:141], v[184:187], v[58:61]
	v_mfma_f32_16x16x32_bf16 v[46:49], v[130:133], v[208:211], v[46:49]
	v_mfma_f32_16x16x32_bf16 v[42:45], v[138:141], v[208:211], v[42:45]
	v_mfma_f32_16x16x32_bf16 v[30:33], v[130:133], v[216:219], v[30:33]
	v_mfma_f32_16x16x32_bf16 v[26:29], v[138:141], v[216:219], v[26:29]
	v_mfma_f32_16x16x32_bf16 v[14:17], v[130:133], v[224:227], v[14:17]
	v_mfma_f32_16x16x32_bf16 v[10:13], v[138:141], v[224:227], v[10:13]
	v_mfma_f32_16x16x32_bf16 v[62:65], v[134:137], v[188:191], v[62:65]
	v_mfma_f32_16x16x32_bf16 v[58:61], v[142:145], v[188:191], v[58:61]
	v_mfma_f32_16x16x32_bf16 v[46:49], v[134:137], v[212:215], v[46:49]
	v_mfma_f32_16x16x32_bf16 v[42:45], v[142:145], v[212:215], v[42:45]
	v_mfma_f32_16x16x32_bf16 v[30:33], v[134:137], v[220:223], v[30:33]
	v_mfma_f32_16x16x32_bf16 v[26:29], v[142:145], v[220:223], v[26:29]
	v_mfma_f32_16x16x32_bf16 v[14:17], v[134:137], v[228:231], v[14:17]
	v_mfma_f32_16x16x32_bf16 v[10:13], v[142:145], v[228:231], v[10:13]
	v_mfma_f32_16x16x32_bf16 v[54:57], v[146:149], v[184:187], v[54:57]
	v_mfma_f32_16x16x32_bf16 v[50:53], v[176:179], v[184:187], v[50:53]
	v_mfma_f32_16x16x32_bf16 v[38:41], v[146:149], v[208:211], v[38:41]
	v_mfma_f32_16x16x32_bf16 v[34:37], v[176:179], v[208:211], v[34:37]
	v_mfma_f32_16x16x32_bf16 v[22:25], v[146:149], v[216:219], v[22:25]
	v_mfma_f32_16x16x32_bf16 v[18:21], v[176:179], v[216:219], v[18:21]
	v_mfma_f32_16x16x32_bf16 v[6:9], v[146:149], v[224:227], v[6:9]
	v_mfma_f32_16x16x32_bf16 v[2:5], v[176:179], v[224:227], v[2:5]
	v_mfma_f32_16x16x32_bf16 v[54:57], v[150:153], v[188:191], v[54:57]
	v_mfma_f32_16x16x32_bf16 v[50:53], v[180:183], v[188:191], v[50:53]
	v_mfma_f32_16x16x32_bf16 v[38:41], v[150:153], v[212:215], v[38:41]
	v_mfma_f32_16x16x32_bf16 v[34:37], v[180:183], v[212:215], v[34:37]
	v_mfma_f32_16x16x32_bf16 v[22:25], v[150:153], v[220:223], v[22:25]
	v_mfma_f32_16x16x32_bf16 v[18:21], v[180:183], v[220:223], v[18:21]
	v_mfma_f32_16x16x32_bf16 v[6:9], v[150:153], v[228:231], v[6:9]
	v_mfma_f32_16x16x32_bf16 v[2:5], v[180:183], v[228:231], v[2:5]
	s_barrier
	s_setprio 0
	s_add_i32 s59, 0, 0x18000
	s_add_i32 s86, 0, 0x1c000
	v_add_u32_e32 v142, s59, v205
	v_add_u32_e32 v180, s86, v205
	ds_read_b128 v[130:133], v142
	ds_read_b128 v[134:137], v142 offset:1024
	ds_read_b128 v[138:141], v142 offset:2048
	ds_read_b128 v[142:145], v142 offset:3072
	ds_read_b128 v[146:149], v180
	ds_read_b128 v[150:153], v180 offset:1024
	ds_read_b128 v[176:179], v180 offset:2048
	ds_read_b128 v[180:183], v180 offset:3072
	s_add_u32 s38, s70, s14
	s_addc_u32 s39, s71, 0
	s_mov_b32 m0, s75
	v_lshl_add_u64 v[240:241], s[38:39], 0, v[170:171]
	ds_read_b128 v[184:187], v207 offset:32768
	ds_read_b128 v[188:191], v207 offset:33792
	ds_read_b128 v[208:211], v207 offset:34816
	ds_read_b128 v[212:215], v207 offset:35840
	ds_read_b128 v[216:219], v207 offset:36864
	ds_read_b128 v[220:223], v207 offset:37888
	ds_read_b128 v[224:227], v207 offset:38912
	ds_read_b128 v[228:231], v207 offset:39936
	global_load_lds_dwordx4 v[240:241], off
	v_lshl_add_u64 v[240:241], s[38:39], 0, v[168:169]
	s_mov_b32 m0, s76
	s_nop 0
	global_load_lds_dwordx4 v[240:241], off
	s_waitcnt vmcnt(8)
	s_waitcnt lgkmcnt(0)
	s_setprio 1
	s_barrier
	v_mfma_f32_16x16x32_bf16 v[126:129], v[130:133], v[184:187], v[126:129]
	v_mfma_f32_16x16x32_bf16 v[122:125], v[138:141], v[184:187], v[122:125]
	v_mfma_f32_16x16x32_bf16 v[110:113], v[130:133], v[208:211], v[110:113]
	v_mfma_f32_16x16x32_bf16 v[106:109], v[138:141], v[208:211], v[106:109]
	v_mfma_f32_16x16x32_bf16 v[94:97], v[130:133], v[216:219], v[94:97]
	v_mfma_f32_16x16x32_bf16 v[90:93], v[138:141], v[216:219], v[90:93]
	v_mfma_f32_16x16x32_bf16 v[78:81], v[130:133], v[224:227], v[78:81]
	v_mfma_f32_16x16x32_bf16 v[74:77], v[138:141], v[224:227], v[74:77]
	v_mfma_f32_16x16x32_bf16 v[126:129], v[134:137], v[188:191], v[126:129]
	v_mfma_f32_16x16x32_bf16 v[122:125], v[142:145], v[188:191], v[122:125]
	v_mfma_f32_16x16x32_bf16 v[110:113], v[134:137], v[212:215], v[110:113]
	v_mfma_f32_16x16x32_bf16 v[106:109], v[142:145], v[212:215], v[106:109]
	v_mfma_f32_16x16x32_bf16 v[94:97], v[134:137], v[220:223], v[94:97]
	v_mfma_f32_16x16x32_bf16 v[90:93], v[142:145], v[220:223], v[90:93]
	v_mfma_f32_16x16x32_bf16 v[78:81], v[134:137], v[228:231], v[78:81]
	v_mfma_f32_16x16x32_bf16 v[74:77], v[142:145], v[228:231], v[74:77]
	v_mfma_f32_16x16x32_bf16 v[118:121], v[146:149], v[184:187], v[118:121]
	v_mfma_f32_16x16x32_bf16 v[114:117], v[176:179], v[184:187], v[114:117]
	v_mfma_f32_16x16x32_bf16 v[102:105], v[146:149], v[208:211], v[102:105]
	v_mfma_f32_16x16x32_bf16 v[98:101], v[176:179], v[208:211], v[98:101]
	v_mfma_f32_16x16x32_bf16 v[86:89], v[146:149], v[216:219], v[86:89]
	v_mfma_f32_16x16x32_bf16 v[82:85], v[176:179], v[216:219], v[82:85]
	v_mfma_f32_16x16x32_bf16 v[70:73], v[146:149], v[224:227], v[70:73]
	v_mfma_f32_16x16x32_bf16 v[66:69], v[176:179], v[224:227], v[66:69]
	v_mfma_f32_16x16x32_bf16 v[118:121], v[150:153], v[188:191], v[118:121]
	v_mfma_f32_16x16x32_bf16 v[114:117], v[180:183], v[188:191], v[114:117]
	v_mfma_f32_16x16x32_bf16 v[102:105], v[150:153], v[212:215], v[102:105]
	v_mfma_f32_16x16x32_bf16 v[98:101], v[180:183], v[212:215], v[98:101]
	v_mfma_f32_16x16x32_bf16 v[86:89], v[150:153], v[220:223], v[86:89]
	v_mfma_f32_16x16x32_bf16 v[82:85], v[180:183], v[220:223], v[82:85]
	v_mfma_f32_16x16x32_bf16 v[70:73], v[150:153], v[228:231], v[70:73]
	v_mfma_f32_16x16x32_bf16 v[66:69], v[180:183], v[228:231], v[66:69]
	s_barrier
; #define PG8_STAGE(bufoff, gbase, voff) do { _Pragma("unroll") for (int _i = 0; _i < 2; ++_i) \
;         __builtin_amdgcn_global_load_lds((const unsigned*)((const char*)(gbase) + (voff)[_i]), (PG8_LAS unsigned*)(lds + (bufoff) + ldsw + _i * 8192), 16, 0, 0); } while (0)
; #define PG8_LDA(dst, b, h) do { _Pragma("unroll") for (int m = 0; m < 4; ++m) _Pragma("unroll") for (int k = 0; k < 2; ++k) dst[m][k] = *(const PG8_LAS bf16x8*)(lds + PG8_SA(b, h) + aoff + m * 2048 + k * 1024); } while (0)
; #define PG8_MMA(ai, bj, At, Bt) do { __builtin_amdgcn_s_setprio(1); _Pragma("unroll") for (int m = 0; m < 4; ++m) _Pragma("unroll") for (int n = 0; n < 2; ++n) _Pragma("unroll") for (int k = 0; k < 2; ++k) \
;         acc[ai][bj][m][n] = __builtin_amdgcn_mfma_f32_16x16x32_bf16(Bt[n][k], At[m][k], acc[ai][bj][m][n], 0, 0, 0); __builtin_amdgcn_s_setprio(0); } while (0)
; #define PG8_WAIT_V(n) asm volatile("s_waitcnt vmcnt(" #n ")" ::: "memory")
; #define PG8_WAIT_L(n) asm volatile("s_waitcnt lgkmcnt(" #n ")" ::: "memory")
; #define PG8_BAR __builtin_amdgcn_s_barrier()
; #define PG8_SCHED __builtin_amdgcn_sched_barrier(0)
; template <class Epi, class Sched, bool ALIGN_EPI = false, bool SP2 = false>
; __device__ __forceinline__ void gemm_phase(PG8_LAS unsigned char* lds, const Gemm g, const Sched& S, const Epi& E, const int tid) {
;     ...
;             PG8_WAIT_V(8); PG8_WAIT_L(0); PG8_BAR; PG8_MMA(0, 0, At, B0); PG8_MMA(0, 1, At, B1); PG8_BAR; PG8_SCHED;
;             PG8_LDA(At, 1, 1); PG8_STAGE(PG8_SB(1, 0), b3, voffB); PG8_STAGE(PG8_SB(1, 1), b3 + hstep, voffB); PG8_STAGE(PG8_SA(1, 0), a3, voffA);
;             PG8_WAIT_V(8); PG8_WAIT_L(0); PG8_BAR; PG8_MMA(1, 0, At, B0); PG8_MMA(1, 1, At, B1); PG8_BAR; PG8_SCHED;
;     ...
;         if constexpr (ALIGN_EPI) { if (wr == 0) PG8_BAR; }
	s_setprio 0
	s_add_i32 s38, s59, s72
	v_lshl_add_u64 v[192:193], v[192:193], 0, s[56:57]
	s_mov_b32 m0, s38
	ds_read_b128 v[184:187], v207 offset:49152
	ds_read_b128 v[188:191], v207 offset:50176
	ds_read_b128 v[208:211], v207 offset:51200
	ds_read_b128 v[212:215], v207 offset:52224
	ds_read_b128 v[216:219], v207 offset:53248
	ds_read_b128 v[220:223], v207 offset:54272
	ds_read_b128 v[224:227], v207 offset:55296
	ds_read_b128 v[228:231], v207 offset:56320
	global_load_lds_dwordx4 v[192:193], off
	v_lshl_add_u64 v[192:193], v[194:195], 0, s[56:57]
	s_add_i32 m0, s38, 0x2000
	s_add_i32 s38, s86, s72
	global_load_lds_dwordx4 v[192:193], off
	v_lshl_add_u64 v[192:193], v[232:233], 0, s[56:57]
	s_mov_b32 m0, s38
	s_nop 0
	global_load_lds_dwordx4 v[192:193], off
	v_lshl_add_u64 v[192:193], v[234:235], 0, s[56:57]
	s_add_i32 m0, s38, 0x2000
	s_nop 0
	global_load_lds_dwordx4 v[192:193], off
	v_lshl_add_u64 v[192:193], v[236:237], 0, s[56:57]
	s_mov_b32 m0, s79
	s_nop 0
	global_load_lds_dwordx4 v[192:193], off
	v_lshl_add_u64 v[192:193], v[238:239], 0, s[56:57]
	s_mov_b32 m0, s80
	s_nop 0
	global_load_lds_dwordx4 v[192:193], off
	s_waitcnt vmcnt(8)
	s_waitcnt lgkmcnt(0)
	s_setprio 1
	s_barrier
	v_mfma_f32_16x16x32_bf16 v[62:65], v[130:133], v[184:187], v[62:65]
	v_mfma_f32_16x16x32_bf16 v[58:61], v[138:141], v[184:187], v[58:61]
	v_mfma_f32_16x16x32_bf16 v[46:49], v[130:133], v[208:211], v[46:49]
	v_mfma_f32_16x16x32_bf16 v[42:45], v[138:141], v[208:211], v[42:45]
	v_mfma_f32_16x16x32_bf16 v[30:33], v[130:133], v[216:219], v[30:33]
	v_mfma_f32_16x16x32_bf16 v[26:29], v[138:141], v[216:219], v[26:29]
	v_mfma_f32_16x16x32_bf16 v[14:17], v[130:133], v[224:227], v[14:17]
	v_mfma_f32_16x16x32_bf16 v[10:13], v[138:141], v[224:227], v[10:13]
	v_mfma_f32_16x16x32_bf16 v[62:65], v[134:137], v[188:191], v[62:65]
	v_mfma_f32_16x16x32_bf16 v[58:61], v[142:145], v[188:191], v[58:61]
	v_mfma_f32_16x16x32_bf16 v[46:49], v[134:137], v[212:215], v[46:49]
	v_mfma_f32_16x16x32_bf16 v[42:45], v[142:145], v[212:215], v[42:45]
	v_mfma_f32_16x16x32_bf16 v[30:33], v[134:137], v[220:223], v[30:33]
	v_mfma_f32_16x16x32_bf16 v[26:29], v[142:145], v[220:223], v[26:29]
	v_mfma_f32_16x16x32_bf16 v[14:17], v[134:137], v[228:231], v[14:17]
	v_mfma_f32_16x16x32_bf16 v[10:13], v[142:145], v[228:231], v[10:13]
	v_mfma_f32_16x16x32_bf16 v[54:57], v[146:149], v[184:187], v[54:57]
	v_mfma_f32_16x16x32_bf16 v[50:53], v[176:179], v[184:187], v[50:53]
	v_mfma_f32_16x16x32_bf16 v[38:41], v[146:149], v[208:211], v[38:41]
	v_mfma_f32_16x16x32_bf16 v[34:37], v[176:179], v[208:211], v[34:37]
	v_mfma_f32_16x16x32_bf16 v[22:25], v[146:149], v[216:219], v[22:25]
	v_mfma_f32_16x16x32_bf16 v[18:21], v[176:179], v[216:219], v[18:21]
	v_mfma_f32_16x16x32_bf16 v[6:9], v[146:149], v[224:227], v[6:9]
	v_mfma_f32_16x16x32_bf16 v[2:5], v[176:179], v[224:227], v[2:5]
	v_mfma_f32_16x16x32_bf16 v[54:57], v[150:153], v[188:191], v[54:57]
	v_mfma_f32_16x16x32_bf16 v[50:53], v[180:183], v[188:191], v[50:53]
	v_mfma_f32_16x16x32_bf16 v[38:41], v[150:153], v[212:215], v[38:41]
	v_mfma_f32_16x16x32_bf16 v[34:37], v[180:183], v[212:215], v[34:37]
	v_mfma_f32_16x16x32_bf16 v[22:25], v[150:153], v[220:223], v[22:25]
	v_mfma_f32_16x16x32_bf16 v[18:21], v[180:183], v[220:223], v[18:21]
	v_mfma_f32_16x16x32_bf16 v[6:9], v[150:153], v[228:231], v[6:9]
	v_mfma_f32_16x16x32_bf16 v[2:5], v[180:183], v[228:231], v[2:5]
	s_barrier
	s_setprio 0
	s_add_u32 s68, s68, 0x100
	s_addc_u32 s69, s69, 0
	s_add_u32 s50, s50, 0x100
	s_addc_u32 s51, s51, 0
	s_cmp_ge_u32 s85, s78
	s_mov_b32 s70, s85
	s_cbranch_scc0 .LBB0_618
	s_and_b64 vcc, exec, s[22:23]
	s_cbranch_vccz .LBB0_621
	s_barrier
